# conv-A moved out of the HBM-bound P4 into P3: waves 1-4 compute it (4 items per lane, all loads in flight) while wave 0 runs S2
# speedup vs baseline: 1.1180x; 1.0016x over previous
; __device__ __forceinline__ float bflo(unsigned w) { return __uint_as_float(w << 16); }
; __device__ __forceinline__ float bfhi(unsigned w) { return __uint_as_float(w & 0xffff0000u); }
; __device__ __forceinline__ void conva_prompt(const bf16_t* z, const float* caw, bf16_t* ycat, int gt, int GT) {
; #pragma unroll 2
;     for (int idx = gt; idx < MP * 128; idx += GT) {
;         const int row = idx >> 7, c8 = (idx & 127) * 8, t = row & (SEQ - 1);
;         const bf16_t* zr = z + (size_t)row * NZ + c8;
;         float conv[8];
; #pragma unroll
;         for (int i = 0; i < 8; ++i) conv[i] = 0.f;
; #pragma unroll
;         for (int j = 0; j < 3; ++j) {
;             const bool ok = t - 2 + j >= 0; const ptrdiff_t ro = (ptrdiff_t)(ok ? j - 2 : 0) * NZ;
;             u32x4 c = *(const u32x4*)(zr + ro + 1024); const u32x4 hh = *(const u32x4*)(zr + ro + 2048);
;             if (!ok) c = (u32x4){0u, 0u, 0u, 0u};
;             const f32x4 w0 = *(const f32x4*)(caw + j * 1024 + c8), w1 = *(const f32x4*)(caw + j * 1024 + c8 + 4);
;             conv[0] += w0.x * (bflo(c.x) * bflo(hh.x)); conv[1] += w0.y * (bfhi(c.x) * bfhi(hh.x)); conv[2] += w0.z * (bflo(c.y) * bflo(hh.y)); conv[3] += w0.w * (bfhi(c.y) * bfhi(hh.y));
;             conv[4] += w1.x * (bflo(c.z) * bflo(hh.z)); conv[5] += w1.y * (bfhi(c.z) * bfhi(hh.z)); conv[6] += w1.z * (bflo(c.w) * bflo(hh.w)); conv[7] += w1.w * (bfhi(c.w) * bfhi(hh.w));
.Lp3_conva:
	v_readfirstlane_b32 s14, v54
	s_lshr_b32 s14, s14, 6
	s_cmp_gt_u32 s14, 4
	s_cbranch_scc1 .LBB0_415
	s_load_dwordx2 s[4:5], s[0:1], 0x98
	s_load_dwordx2 s[8:9], s[0:1], 0x58
	s_mul_i32 s14, s92, 0x3000
	s_lshr_b32 s15, s49, 11
	s_lshl_b32 s15, s15, 8
	s_add_i32 s15, s15, s2
	s_lshl_b32 s15, s15, 10
	s_mov_b32 s10, 0xffff0000
	s_mov_b32 s11, 0xbfb8aa3b
	v_add_u32_e32 v33, 0xffffffc0, v54
	v_and_b32_e32 v32, 0x7f, v33
	v_lshlrev_b32_e32 v34, 5, v32
	v_lshlrev_b32_e32 v32, 4, v32
	v_add_u32_e32 v38, 0x1000, v34
	v_add_u32_e32 v39, 0x2000, v34
	v_add_u32_e32 v52, 0x1000, v32
	v_add_u32_e32 v33, s15, v33
	s_waitcnt lgkmcnt(0)
	s_add_u32 s6, s4, 0x20300000
	s_addc_u32 s7, s5, 0
	s_add_u32 s4, s4, 0x13c00000
	s_addc_u32 s5, s5, 0
	s_add_u32 s8, s8, s14
	s_addc_u32 s9, s9, 0
	global_load_dwordx4 v[8:11], v34, s[8:9]
	global_load_dwordx4 v[12:15], v34, s[8:9] offset:16
	global_load_dwordx4 v[16:19], v38, s[8:9]
	global_load_dwordx4 v[20:23], v38, s[8:9] offset:16
	global_load_dwordx4 v[24:27], v39, s[8:9]
	global_load_dwordx4 v[28:31], v39, s[8:9] offset:16
	v_lshrrev_b32_e32 v34, 7, v33
	v_and_b32_e32 v97, 0x7ff, v34
	v_lshl_add_u32 v35, v34, 14, v52
	v_min_u32_e32 v36, 2, v97
	v_min_u32_e32 v37, 1, v97
	v_lshlrev_b32_e32 v36, 14, v36
	v_lshlrev_b32_e32 v37, 14, v37
	v_sub_u32_e32 v36, v35, v36
	v_sub_u32_e32 v37, v35, v37
	v_lshl_add_u32 v96, v34, 12, v32
	global_load_dwordx4 v[64:67], v36, s[4:5] offset:-2048
	global_load_dwordx4 v[68:71], v36, s[4:5]
	global_load_dwordx4 v[72:75], v37, s[4:5] offset:-2048
	global_load_dwordx4 v[76:79], v37, s[4:5]
	global_load_dwordx4 v[80:83], v35, s[4:5] offset:-2048
	global_load_dwordx4 v[84:87], v35, s[4:5]
	global_load_dwordx4 v[88:91], v35, s[4:5] offset:-4096
	global_load_dwordx4 v[92:95], v35, s[4:5] offset:2048
	v_add_u32_e32 v33, 0x100, v33
	v_lshrrev_b32_e32 v34, 7, v33
	v_and_b32_e32 v133, 0x7ff, v34
	v_lshl_add_u32 v35, v34, 14, v52
	v_min_u32_e32 v36, 2, v133
	v_min_u32_e32 v37, 1, v133
	v_lshlrev_b32_e32 v36, 14, v36
	v_lshlrev_b32_e32 v37, 14, v37
	v_sub_u32_e32 v36, v35, v36
	v_sub_u32_e32 v37, v35, v37
	v_lshl_add_u32 v132, v34, 12, v32
	global_load_dwordx4 v[100:103], v36, s[4:5] offset:-2048
	global_load_dwordx4 v[104:107], v36, s[4:5]
	global_load_dwordx4 v[108:111], v37, s[4:5] offset:-2048
	global_load_dwordx4 v[112:115], v37, s[4:5]
	global_load_dwordx4 v[116:119], v35, s[4:5] offset:-2048
	global_load_dwordx4 v[120:123], v35, s[4:5]
	global_load_dwordx4 v[124:127], v35, s[4:5] offset:-4096
	global_load_dwordx4 v[128:131], v35, s[4:5] offset:2048
	v_add_u32_e32 v33, 0x100, v33
	v_lshrrev_b32_e32 v34, 7, v33
	v_and_b32_e32 v233, 0x7ff, v34
	v_lshl_add_u32 v35, v34, 14, v52
	v_min_u32_e32 v36, 2, v233
	v_min_u32_e32 v37, 1, v233
	v_lshlrev_b32_e32 v36, 14, v36
	v_lshlrev_b32_e32 v37, 14, v37
	v_sub_u32_e32 v36, v35, v36
	v_sub_u32_e32 v37, v35, v37
	v_lshl_add_u32 v232, v34, 12, v32
	global_load_dwordx4 v[200:203], v36, s[4:5] offset:-2048
	global_load_dwordx4 v[204:207], v36, s[4:5]
	global_load_dwordx4 v[208:211], v37, s[4:5] offset:-2048
	global_load_dwordx4 v[212:215], v37, s[4:5]
	global_load_dwordx4 v[216:219], v35, s[4:5] offset:-2048
	global_load_dwordx4 v[220:223], v35, s[4:5]
	global_load_dwordx4 v[224:227], v35, s[4:5] offset:-4096
	global_load_dwordx4 v[228:231], v35, s[4:5] offset:2048
	v_add_u32_e32 v33, 0x100, v33
	v_lshrrev_b32_e32 v34, 7, v33
	v_and_b32_e32 v189, 0x7ff, v34
	v_lshl_add_u32 v35, v34, 14, v52
	v_min_u32_e32 v36, 2, v189
	v_min_u32_e32 v37, 1, v189
	v_lshlrev_b32_e32 v36, 14, v36
	v_lshlrev_b32_e32 v37, 14, v37
	v_sub_u32_e32 v36, v35, v36
	v_sub_u32_e32 v37, v35, v37
	v_lshl_add_u32 v188, v34, 12, v32
	global_load_dwordx4 v[156:159], v36, s[4:5] offset:-2048
	global_load_dwordx4 v[160:163], v36, s[4:5]
	global_load_dwordx4 v[164:167], v37, s[4:5] offset:-2048
	global_load_dwordx4 v[168:171], v37, s[4:5]
	global_load_dwordx4 v[172:175], v35, s[4:5] offset:-2048
	global_load_dwordx4 v[176:179], v35, s[4:5]
	global_load_dwordx4 v[180:183], v35, s[4:5] offset:-4096
	global_load_dwordx4 v[184:187], v35, s[4:5] offset:2048
	v_add_u32_e32 v33, 0x100, v33
	s_waitcnt vmcnt(24)
	v_cmp_lt_u32_e32 vcc, 1, v97
	v_lshlrev_b32_e32 v144, 16, v68
	v_and_b32_e32 v145, s10, v68
	v_lshlrev_b32_e32 v146, 16, v69
	v_and_b32_e32 v147, s10, v69
	v_lshlrev_b32_e32 v148, 16, v70
	v_and_b32_e32 v149, s10, v70
	v_lshlrev_b32_e32 v150, 16, v71
	v_and_b32_e32 v151, s10, v71
	v_cndmask_b32_e32 v64, 0, v64, vcc
	v_cndmask_b32_e32 v65, 0, v65, vcc
	v_cndmask_b32_e32 v66, 0, v66, vcc
	v_cndmask_b32_e32 v67, 0, v67, vcc
	v_cmp_ne_u32_e32 vcc, 0, v97
	v_lshlrev_b32_e32 v136, 16, v64
	v_and_b32_e32 v137, s10, v64
	v_lshlrev_b32_e32 v138, 16, v65
	v_and_b32_e32 v139, s10, v65
	v_lshlrev_b32_e32 v140, 16, v66
	v_and_b32_e32 v141, s10, v66
	v_lshlrev_b32_e32 v142, 16, v67
	v_and_b32_e32 v143, s10, v67
	v_cndmask_b32_e32 v72, 0, v72, vcc
	v_cndmask_b32_e32 v73, 0, v73, vcc
	v_cndmask_b32_e32 v74, 0, v74, vcc
	v_cndmask_b32_e32 v75, 0, v75, vcc
	v_pk_mul_f32 v[136:137], v[136:137], v[144:145]
	v_pk_mul_f32 v[138:139], v[138:139], v[146:147]
	v_pk_mul_f32 v[140:141], v[140:141], v[148:149]
	v_pk_mul_f32 v[142:143], v[142:143], v[150:151]
	v_pk_mul_f32 v[236:237], v[8:9], v[136:137]
	v_pk_mul_f32 v[238:239], v[10:11], v[138:139]
	v_pk_mul_f32 v[240:241], v[12:13], v[140:141]
	v_pk_mul_f32 v[242:243], v[14:15], v[142:143]
	v_lshlrev_b32_e32 v136, 16, v72
	v_and_b32_e32 v137, s10, v72
	v_lshlrev_b32_e32 v138, 16, v73
	v_and_b32_e32 v139, s10, v73
	v_lshlrev_b32_e32 v140, 16, v74
	v_and_b32_e32 v141, s10, v74
	v_lshlrev_b32_e32 v142, 16, v75
	v_and_b32_e32 v143, s10, v75
; __device__ __forceinline__ float bflo(unsigned w) { return __uint_as_float(w << 16); }
; __device__ __forceinline__ float bfhi(unsigned w) { return __uint_as_float(w & 0xffff0000u); }
; __device__ __forceinline__ float silu_f(float x) { return x * rcp_f(1.f + exp_f(-x)); }
; __device__ __forceinline__ u32x4 pack8(const float* v) { u32x4 o; o.x = pk2(v[0], v[1]); o.y = pk2(v[2], v[3]); o.z = pk2(v[4], v[5]); o.w = pk2(v[6], v[7]); return o; }
; __device__ __forceinline__ void conva_prompt(const bf16_t* z, const float* caw, bf16_t* ycat, int gt, int GT) {
;     ...
;         for (int j = 0; j < 3; ++j) {
;             const bool ok = t - 2 + j >= 0; const ptrdiff_t ro = (ptrdiff_t)(ok ? j - 2 : 0) * NZ;
;             u32x4 c = *(const u32x4*)(zr + ro + 1024); const u32x4 hh = *(const u32x4*)(zr + ro + 2048);
;             if (!ok) c = (u32x4){0u, 0u, 0u, 0u};
;             const f32x4 w0 = *(const f32x4*)(caw + j * 1024 + c8), w1 = *(const f32x4*)(caw + j * 1024 + c8 + 4);
;             conv[0] += w0.x * (bflo(c.x) * bflo(hh.x)); conv[1] += w0.y * (bfhi(c.x) * bfhi(hh.x)); conv[2] += w0.z * (bflo(c.y) * bflo(hh.y)); conv[3] += w0.w * (bfhi(c.y) * bfhi(hh.y));
;             conv[4] += w1.x * (bflo(c.z) * bflo(hh.z)); conv[5] += w1.y * (bfhi(c.z) * bfhi(hh.z)); conv[6] += w1.z * (bflo(c.w) * bflo(hh.w)); conv[7] += w1.w * (bfhi(c.w) * bfhi(hh.w));
;         }
;         const u32x4 bb = *(const u32x4*)zr, gg = *(const u32x4*)(zr + 3072);
;         float y[8];
;         y[0] = bflo(bb.x) * conv[0] * silu_f(bflo(gg.x)); y[1] = bfhi(bb.x) * conv[1] * silu_f(bfhi(gg.x)); y[2] = bflo(bb.y) * conv[2] * silu_f(bflo(gg.y)); y[3] = bfhi(bb.y) * conv[3] * silu_f(bfhi(gg.y));
;         y[4] = bflo(bb.z) * conv[4] * silu_f(bflo(gg.z)); y[5] = bfhi(bb.z) * conv[5] * silu_f(bfhi(gg.z)); y[6] = bflo(bb.w) * conv[6] * silu_f(bflo(gg.w)); y[7] = bfhi(bb.w) * conv[7] * silu_f(bfhi(gg.w));
;         *(u32x4*)(ycat + (size_t)row * DM + c8) = pack8(y);
	v_lshlrev_b32_e32 v144, 16, v76
	v_and_b32_e32 v145, s10, v76
	v_lshlrev_b32_e32 v146, 16, v77
	v_and_b32_e32 v147, s10, v77
	v_lshlrev_b32_e32 v148, 16, v78
	v_and_b32_e32 v149, s10, v78
	v_lshlrev_b32_e32 v150, 16, v79
	v_and_b32_e32 v151, s10, v79
	v_pk_mul_f32 v[136:137], v[136:137], v[144:145]
	v_pk_mul_f32 v[138:139], v[138:139], v[146:147]
	v_pk_mul_f32 v[140:141], v[140:141], v[148:149]
	v_pk_mul_f32 v[142:143], v[142:143], v[150:151]
	v_pk_fma_f32 v[236:237], v[16:17], v[136:137], v[236:237]
	v_pk_fma_f32 v[238:239], v[18:19], v[138:139], v[238:239]
	v_pk_fma_f32 v[240:241], v[20:21], v[140:141], v[240:241]
	v_pk_fma_f32 v[242:243], v[22:23], v[142:143], v[242:243]
	v_lshlrev_b32_e32 v136, 16, v80
	v_and_b32_e32 v137, s10, v80
	v_lshlrev_b32_e32 v138, 16, v81
	v_and_b32_e32 v139, s10, v81
	v_lshlrev_b32_e32 v140, 16, v82
	v_and_b32_e32 v141, s10, v82
	v_lshlrev_b32_e32 v142, 16, v83
	v_and_b32_e32 v143, s10, v83
	v_lshlrev_b32_e32 v144, 16, v84
	v_and_b32_e32 v145, s10, v84
	v_lshlrev_b32_e32 v146, 16, v85
	v_and_b32_e32 v147, s10, v85
	v_lshlrev_b32_e32 v148, 16, v86
	v_and_b32_e32 v149, s10, v86
	v_lshlrev_b32_e32 v150, 16, v87
	v_and_b32_e32 v151, s10, v87
	v_pk_mul_f32 v[136:137], v[136:137], v[144:145]
	v_pk_mul_f32 v[138:139], v[138:139], v[146:147]
	v_pk_mul_f32 v[140:141], v[140:141], v[148:149]
	v_pk_mul_f32 v[142:143], v[142:143], v[150:151]
	v_pk_fma_f32 v[236:237], v[24:25], v[136:137], v[236:237]
	v_pk_fma_f32 v[238:239], v[26:27], v[138:139], v[238:239]
	v_pk_fma_f32 v[240:241], v[28:29], v[140:141], v[240:241]
	v_pk_fma_f32 v[242:243], v[30:31], v[142:143], v[242:243]
	v_lshlrev_b32_e32 v144, 16, v92
	v_and_b32_e32 v145, s10, v92
	v_lshlrev_b32_e32 v146, 16, v93
	v_and_b32_e32 v147, s10, v93
	v_lshlrev_b32_e32 v148, 16, v94
	v_and_b32_e32 v149, s10, v94
	v_lshlrev_b32_e32 v150, 16, v95
	v_and_b32_e32 v151, s10, v95
	v_mul_f32_e32 v136, s11, v144
	v_mul_f32_e32 v137, s11, v145
	v_mul_f32_e32 v138, s11, v146
	v_mul_f32_e32 v139, s11, v147
	v_mul_f32_e32 v140, s11, v148
	v_mul_f32_e32 v141, s11, v149
	v_mul_f32_e32 v142, s11, v150
	v_mul_f32_e32 v143, s11, v151
	v_exp_f32_e32 v136, v136
	v_exp_f32_e32 v137, v137
	v_exp_f32_e32 v138, v138
	v_exp_f32_e32 v139, v139
	v_exp_f32_e32 v140, v140
	v_exp_f32_e32 v141, v141
	v_exp_f32_e32 v142, v142
	v_exp_f32_e32 v143, v143
	v_lshlrev_b32_e32 v244, 16, v88
	v_and_b32_e32 v245, s10, v88
	v_lshlrev_b32_e32 v246, 16, v89
	v_and_b32_e32 v247, s10, v89
	v_lshlrev_b32_e32 v248, 16, v90
	v_and_b32_e32 v249, s10, v90
	v_lshlrev_b32_e32 v250, 16, v91
	v_and_b32_e32 v251, s10, v91
	v_add_f32_e32 v136, 1.0, v136
	v_add_f32_e32 v137, 1.0, v137
	v_add_f32_e32 v138, 1.0, v138
	v_add_f32_e32 v139, 1.0, v139
	v_add_f32_e32 v140, 1.0, v140
	v_add_f32_e32 v141, 1.0, v141
	v_add_f32_e32 v142, 1.0, v142
	v_add_f32_e32 v143, 1.0, v143
	v_rcp_f32_e32 v136, v136
	v_rcp_f32_e32 v137, v137
	v_rcp_f32_e32 v138, v138
	v_rcp_f32_e32 v139, v139
	v_rcp_f32_e32 v140, v140
	v_rcp_f32_e32 v141, v141
	v_rcp_f32_e32 v142, v142
	v_rcp_f32_e32 v143, v143
	v_pk_mul_f32 v[244:245], v[244:245], v[236:237]
	v_pk_mul_f32 v[246:247], v[246:247], v[238:239]
	v_pk_mul_f32 v[248:249], v[248:249], v[240:241]
	v_pk_mul_f32 v[250:251], v[250:251], v[242:243]
	v_pk_mul_f32 v[144:145], v[144:145], v[136:137]
	v_pk_mul_f32 v[146:147], v[146:147], v[138:139]
	v_pk_mul_f32 v[148:149], v[148:149], v[140:141]
	v_pk_mul_f32 v[150:151], v[150:151], v[142:143]
	v_pk_mul_f32 v[244:245], v[244:245], v[144:145]
	v_pk_mul_f32 v[246:247], v[246:247], v[146:147]
	v_pk_mul_f32 v[248:249], v[248:249], v[148:149]
	v_pk_mul_f32 v[250:251], v[250:251], v[150:151]
	v_cvt_pk_bf16_f32 v48, v244, v245
	v_cvt_pk_bf16_f32 v49, v246, v247
	v_cvt_pk_bf16_f32 v50, v248, v249
	v_cvt_pk_bf16_f32 v51, v250, v251
	global_store_dwordx4 v96, v[48:51], s[6:7]
	s_waitcnt vmcnt(17)
	v_cmp_lt_u32_e32 vcc, 1, v133
	v_lshlrev_b32_e32 v144, 16, v104
	v_and_b32_e32 v145, s10, v104
	v_lshlrev_b32_e32 v146, 16, v105
	v_and_b32_e32 v147, s10, v105
	v_lshlrev_b32_e32 v148, 16, v106
	v_and_b32_e32 v149, s10, v106
	v_lshlrev_b32_e32 v150, 16, v107
	v_and_b32_e32 v151, s10, v107
	v_cndmask_b32_e32 v100, 0, v100, vcc
	v_cndmask_b32_e32 v101, 0, v101, vcc
	v_cndmask_b32_e32 v102, 0, v102, vcc
	v_cndmask_b32_e32 v103, 0, v103, vcc
	v_cmp_ne_u32_e32 vcc, 0, v133
	v_lshlrev_b32_e32 v136, 16, v100
	v_and_b32_e32 v137, s10, v100
	v_lshlrev_b32_e32 v138, 16, v101
	v_and_b32_e32 v139, s10, v101
	v_lshlrev_b32_e32 v140, 16, v102
	v_and_b32_e32 v141, s10, v102
	v_lshlrev_b32_e32 v142, 16, v103
	v_and_b32_e32 v143, s10, v103
	v_cndmask_b32_e32 v108, 0, v108, vcc
	v_cndmask_b32_e32 v109, 0, v109, vcc
	v_cndmask_b32_e32 v110, 0, v110, vcc
	v_cndmask_b32_e32 v111, 0, v111, vcc
	v_pk_mul_f32 v[136:137], v[136:137], v[144:145]
	v_pk_mul_f32 v[138:139], v[138:139], v[146:147]
	v_pk_mul_f32 v[140:141], v[140:141], v[148:149]
	v_pk_mul_f32 v[142:143], v[142:143], v[150:151]
	v_pk_mul_f32 v[236:237], v[8:9], v[136:137]
	v_pk_mul_f32 v[238:239], v[10:11], v[138:139]
	v_pk_mul_f32 v[240:241], v[12:13], v[140:141]
	v_pk_mul_f32 v[242:243], v[14:15], v[142:143]
	v_lshlrev_b32_e32 v136, 16, v108
	v_and_b32_e32 v137, s10, v108
	v_lshlrev_b32_e32 v138, 16, v109
	v_and_b32_e32 v139, s10, v109
	v_lshlrev_b32_e32 v140, 16, v110
	v_and_b32_e32 v141, s10, v110
	v_lshlrev_b32_e32 v142, 16, v111
	v_and_b32_e32 v143, s10, v111
	v_lshlrev_b32_e32 v144, 16, v112
	v_and_b32_e32 v145, s10, v112
	v_lshlrev_b32_e32 v146, 16, v113
	v_and_b32_e32 v147, s10, v113
	v_lshlrev_b32_e32 v148, 16, v114
	v_and_b32_e32 v149, s10, v114
	v_lshlrev_b32_e32 v150, 16, v115
	v_and_b32_e32 v151, s10, v115
; __device__ __forceinline__ float bflo(unsigned w) { return __uint_as_float(w << 16); }
; __device__ __forceinline__ float bfhi(unsigned w) { return __uint_as_float(w & 0xffff0000u); }
; __device__ __forceinline__ float silu_f(float x) { return x * rcp_f(1.f + exp_f(-x)); }
; __device__ __forceinline__ u32x4 pack8(const float* v) { u32x4 o; o.x = pk2(v[0], v[1]); o.y = pk2(v[2], v[3]); o.z = pk2(v[4], v[5]); o.w = pk2(v[6], v[7]); return o; }
; __device__ __forceinline__ void conva_prompt(const bf16_t* z, const float* caw, bf16_t* ycat, int gt, int GT) {
;     ...
;         for (int j = 0; j < 3; ++j) {
;             const bool ok = t - 2 + j >= 0; const ptrdiff_t ro = (ptrdiff_t)(ok ? j - 2 : 0) * NZ;
;             u32x4 c = *(const u32x4*)(zr + ro + 1024); const u32x4 hh = *(const u32x4*)(zr + ro + 2048);
;             if (!ok) c = (u32x4){0u, 0u, 0u, 0u};
;             const f32x4 w0 = *(const f32x4*)(caw + j * 1024 + c8), w1 = *(const f32x4*)(caw + j * 1024 + c8 + 4);
;             conv[0] += w0.x * (bflo(c.x) * bflo(hh.x)); conv[1] += w0.y * (bfhi(c.x) * bfhi(hh.x)); conv[2] += w0.z * (bflo(c.y) * bflo(hh.y)); conv[3] += w0.w * (bfhi(c.y) * bfhi(hh.y));
;             conv[4] += w1.x * (bflo(c.z) * bflo(hh.z)); conv[5] += w1.y * (bfhi(c.z) * bfhi(hh.z)); conv[6] += w1.z * (bflo(c.w) * bflo(hh.w)); conv[7] += w1.w * (bfhi(c.w) * bfhi(hh.w));
;         }
;         const u32x4 bb = *(const u32x4*)zr, gg = *(const u32x4*)(zr + 3072);
;         float y[8];
;         y[0] = bflo(bb.x) * conv[0] * silu_f(bflo(gg.x)); y[1] = bfhi(bb.x) * conv[1] * silu_f(bfhi(gg.x)); y[2] = bflo(bb.y) * conv[2] * silu_f(bflo(gg.y)); y[3] = bfhi(bb.y) * conv[3] * silu_f(bfhi(gg.y));
;         y[4] = bflo(bb.z) * conv[4] * silu_f(bflo(gg.z)); y[5] = bfhi(bb.z) * conv[5] * silu_f(bfhi(gg.z)); y[6] = bflo(bb.w) * conv[6] * silu_f(bflo(gg.w)); y[7] = bfhi(bb.w) * conv[7] * silu_f(bfhi(gg.w));
;         *(u32x4*)(ycat + (size_t)row * DM + c8) = pack8(y);
	v_pk_mul_f32 v[136:137], v[136:137], v[144:145]
	v_pk_mul_f32 v[138:139], v[138:139], v[146:147]
	v_pk_mul_f32 v[140:141], v[140:141], v[148:149]
	v_pk_mul_f32 v[142:143], v[142:143], v[150:151]
	v_pk_fma_f32 v[236:237], v[16:17], v[136:137], v[236:237]
	v_pk_fma_f32 v[238:239], v[18:19], v[138:139], v[238:239]
	v_pk_fma_f32 v[240:241], v[20:21], v[140:141], v[240:241]
	v_pk_fma_f32 v[242:243], v[22:23], v[142:143], v[242:243]
	v_lshlrev_b32_e32 v136, 16, v116
	v_and_b32_e32 v137, s10, v116
	v_lshlrev_b32_e32 v138, 16, v117
	v_and_b32_e32 v139, s10, v117
	v_lshlrev_b32_e32 v140, 16, v118
	v_and_b32_e32 v141, s10, v118
	v_lshlrev_b32_e32 v142, 16, v119
	v_and_b32_e32 v143, s10, v119
	v_lshlrev_b32_e32 v144, 16, v120
	v_and_b32_e32 v145, s10, v120
	v_lshlrev_b32_e32 v146, 16, v121
	v_and_b32_e32 v147, s10, v121
	v_lshlrev_b32_e32 v148, 16, v122
	v_and_b32_e32 v149, s10, v122
	v_lshlrev_b32_e32 v150, 16, v123
	v_and_b32_e32 v151, s10, v123
	v_pk_mul_f32 v[136:137], v[136:137], v[144:145]
	v_pk_mul_f32 v[138:139], v[138:139], v[146:147]
	v_pk_mul_f32 v[140:141], v[140:141], v[148:149]
	v_pk_mul_f32 v[142:143], v[142:143], v[150:151]
	v_pk_fma_f32 v[236:237], v[24:25], v[136:137], v[236:237]
	v_pk_fma_f32 v[238:239], v[26:27], v[138:139], v[238:239]
	v_pk_fma_f32 v[240:241], v[28:29], v[140:141], v[240:241]
	v_pk_fma_f32 v[242:243], v[30:31], v[142:143], v[242:243]
	v_lshlrev_b32_e32 v144, 16, v128
	v_and_b32_e32 v145, s10, v128
	v_lshlrev_b32_e32 v146, 16, v129
	v_and_b32_e32 v147, s10, v129
	v_lshlrev_b32_e32 v148, 16, v130
	v_and_b32_e32 v149, s10, v130
	v_lshlrev_b32_e32 v150, 16, v131
	v_and_b32_e32 v151, s10, v131
	v_mul_f32_e32 v136, s11, v144
	v_mul_f32_e32 v137, s11, v145
	v_mul_f32_e32 v138, s11, v146
	v_mul_f32_e32 v139, s11, v147
	v_mul_f32_e32 v140, s11, v148
	v_mul_f32_e32 v141, s11, v149
	v_mul_f32_e32 v142, s11, v150
	v_mul_f32_e32 v143, s11, v151
	v_exp_f32_e32 v136, v136
	v_exp_f32_e32 v137, v137
	v_exp_f32_e32 v138, v138
	v_exp_f32_e32 v139, v139
	v_exp_f32_e32 v140, v140
	v_exp_f32_e32 v141, v141
	v_exp_f32_e32 v142, v142
	v_exp_f32_e32 v143, v143
	v_lshlrev_b32_e32 v244, 16, v124
	v_and_b32_e32 v245, s10, v124
	v_lshlrev_b32_e32 v246, 16, v125
	v_and_b32_e32 v247, s10, v125
	v_lshlrev_b32_e32 v248, 16, v126
	v_and_b32_e32 v249, s10, v126
	v_lshlrev_b32_e32 v250, 16, v127
	v_and_b32_e32 v251, s10, v127
	v_add_f32_e32 v136, 1.0, v136
	v_add_f32_e32 v137, 1.0, v137
	v_add_f32_e32 v138, 1.0, v138
	v_add_f32_e32 v139, 1.0, v139
	v_add_f32_e32 v140, 1.0, v140
	v_add_f32_e32 v141, 1.0, v141
	v_add_f32_e32 v142, 1.0, v142
	v_add_f32_e32 v143, 1.0, v143
	v_rcp_f32_e32 v136, v136
	v_rcp_f32_e32 v137, v137
	v_rcp_f32_e32 v138, v138
	v_rcp_f32_e32 v139, v139
	v_rcp_f32_e32 v140, v140
	v_rcp_f32_e32 v141, v141
	v_rcp_f32_e32 v142, v142
	v_rcp_f32_e32 v143, v143
	v_pk_mul_f32 v[244:245], v[244:245], v[236:237]
	v_pk_mul_f32 v[246:247], v[246:247], v[238:239]
	v_pk_mul_f32 v[248:249], v[248:249], v[240:241]
	v_pk_mul_f32 v[250:251], v[250:251], v[242:243]
	v_pk_mul_f32 v[144:145], v[144:145], v[136:137]
	v_pk_mul_f32 v[146:147], v[146:147], v[138:139]
	v_pk_mul_f32 v[148:149], v[148:149], v[140:141]
	v_pk_mul_f32 v[150:151], v[150:151], v[142:143]
	v_pk_mul_f32 v[244:245], v[244:245], v[144:145]
	v_pk_mul_f32 v[246:247], v[246:247], v[146:147]
	v_pk_mul_f32 v[248:249], v[248:249], v[148:149]
	v_pk_mul_f32 v[250:251], v[250:251], v[150:151]
	v_cvt_pk_bf16_f32 v48, v244, v245
	v_cvt_pk_bf16_f32 v49, v246, v247
	v_cvt_pk_bf16_f32 v50, v248, v249
	v_cvt_pk_bf16_f32 v51, v250, v251
	global_store_dwordx4 v132, v[48:51], s[6:7]
	s_waitcnt vmcnt(10)
	v_cmp_lt_u32_e32 vcc, 1, v233
	v_lshlrev_b32_e32 v144, 16, v204
	v_and_b32_e32 v145, s10, v204
	v_lshlrev_b32_e32 v146, 16, v205
	v_and_b32_e32 v147, s10, v205
	v_lshlrev_b32_e32 v148, 16, v206
	v_and_b32_e32 v149, s10, v206
	v_lshlrev_b32_e32 v150, 16, v207
	v_and_b32_e32 v151, s10, v207
	v_cndmask_b32_e32 v200, 0, v200, vcc
	v_cndmask_b32_e32 v201, 0, v201, vcc
	v_cndmask_b32_e32 v202, 0, v202, vcc
	v_cndmask_b32_e32 v203, 0, v203, vcc
	v_cmp_ne_u32_e32 vcc, 0, v233
	v_lshlrev_b32_e32 v136, 16, v200
	v_and_b32_e32 v137, s10, v200
	v_lshlrev_b32_e32 v138, 16, v201
	v_and_b32_e32 v139, s10, v201
	v_lshlrev_b32_e32 v140, 16, v202
	v_and_b32_e32 v141, s10, v202
	v_lshlrev_b32_e32 v142, 16, v203
	v_and_b32_e32 v143, s10, v203
	v_cndmask_b32_e32 v208, 0, v208, vcc
	v_cndmask_b32_e32 v209, 0, v209, vcc
	v_cndmask_b32_e32 v210, 0, v210, vcc
	v_cndmask_b32_e32 v211, 0, v211, vcc
	v_pk_mul_f32 v[136:137], v[136:137], v[144:145]
	v_pk_mul_f32 v[138:139], v[138:139], v[146:147]
	v_pk_mul_f32 v[140:141], v[140:141], v[148:149]
	v_pk_mul_f32 v[142:143], v[142:143], v[150:151]
	v_pk_mul_f32 v[236:237], v[8:9], v[136:137]
	v_pk_mul_f32 v[238:239], v[10:11], v[138:139]
	v_pk_mul_f32 v[240:241], v[12:13], v[140:141]
	v_pk_mul_f32 v[242:243], v[14:15], v[142:143]
	v_lshlrev_b32_e32 v136, 16, v208
	v_and_b32_e32 v137, s10, v208
	v_lshlrev_b32_e32 v138, 16, v209
	v_and_b32_e32 v139, s10, v209
	v_lshlrev_b32_e32 v140, 16, v210
	v_and_b32_e32 v141, s10, v210
	v_lshlrev_b32_e32 v142, 16, v211
	v_and_b32_e32 v143, s10, v211
	v_lshlrev_b32_e32 v144, 16, v212
	v_and_b32_e32 v145, s10, v212
	v_lshlrev_b32_e32 v146, 16, v213
	v_and_b32_e32 v147, s10, v213
	v_lshlrev_b32_e32 v148, 16, v214
	v_and_b32_e32 v149, s10, v214
	v_lshlrev_b32_e32 v150, 16, v215
	v_and_b32_e32 v151, s10, v215
	v_pk_mul_f32 v[136:137], v[136:137], v[144:145]
	v_pk_mul_f32 v[138:139], v[138:139], v[146:147]
	v_pk_mul_f32 v[140:141], v[140:141], v[148:149]
	v_pk_mul_f32 v[142:143], v[142:143], v[150:151]
	v_pk_fma_f32 v[236:237], v[16:17], v[136:137], v[236:237]
; __device__ __forceinline__ float bflo(unsigned w) { return __uint_as_float(w << 16); }
; __device__ __forceinline__ float bfhi(unsigned w) { return __uint_as_float(w & 0xffff0000u); }
; __device__ __forceinline__ float silu_f(float x) { return x * rcp_f(1.f + exp_f(-x)); }
; __device__ __forceinline__ u32x4 pack8(const float* v) { u32x4 o; o.x = pk2(v[0], v[1]); o.y = pk2(v[2], v[3]); o.z = pk2(v[4], v[5]); o.w = pk2(v[6], v[7]); return o; }
; __device__ __forceinline__ void conva_prompt(const bf16_t* z, const float* caw, bf16_t* ycat, int gt, int GT) {
;     ...
;         for (int j = 0; j < 3; ++j) {
;             const bool ok = t - 2 + j >= 0; const ptrdiff_t ro = (ptrdiff_t)(ok ? j - 2 : 0) * NZ;
;             u32x4 c = *(const u32x4*)(zr + ro + 1024); const u32x4 hh = *(const u32x4*)(zr + ro + 2048);
;             if (!ok) c = (u32x4){0u, 0u, 0u, 0u};
;             const f32x4 w0 = *(const f32x4*)(caw + j * 1024 + c8), w1 = *(const f32x4*)(caw + j * 1024 + c8 + 4);
;             conv[0] += w0.x * (bflo(c.x) * bflo(hh.x)); conv[1] += w0.y * (bfhi(c.x) * bfhi(hh.x)); conv[2] += w0.z * (bflo(c.y) * bflo(hh.y)); conv[3] += w0.w * (bfhi(c.y) * bfhi(hh.y));
;             conv[4] += w1.x * (bflo(c.z) * bflo(hh.z)); conv[5] += w1.y * (bfhi(c.z) * bfhi(hh.z)); conv[6] += w1.z * (bflo(c.w) * bflo(hh.w)); conv[7] += w1.w * (bfhi(c.w) * bfhi(hh.w));
;         }
;         const u32x4 bb = *(const u32x4*)zr, gg = *(const u32x4*)(zr + 3072);
;         float y[8];
;         y[0] = bflo(bb.x) * conv[0] * silu_f(bflo(gg.x)); y[1] = bfhi(bb.x) * conv[1] * silu_f(bfhi(gg.x)); y[2] = bflo(bb.y) * conv[2] * silu_f(bflo(gg.y)); y[3] = bfhi(bb.y) * conv[3] * silu_f(bfhi(gg.y));
;         y[4] = bflo(bb.z) * conv[4] * silu_f(bflo(gg.z)); y[5] = bfhi(bb.z) * conv[5] * silu_f(bfhi(gg.z)); y[6] = bflo(bb.w) * conv[6] * silu_f(bflo(gg.w)); y[7] = bfhi(bb.w) * conv[7] * silu_f(bfhi(gg.w));
;         *(u32x4*)(ycat + (size_t)row * DM + c8) = pack8(y);
	v_pk_fma_f32 v[238:239], v[18:19], v[138:139], v[238:239]
	v_pk_fma_f32 v[240:241], v[20:21], v[140:141], v[240:241]
	v_pk_fma_f32 v[242:243], v[22:23], v[142:143], v[242:243]
	v_lshlrev_b32_e32 v136, 16, v216
	v_and_b32_e32 v137, s10, v216
	v_lshlrev_b32_e32 v138, 16, v217
	v_and_b32_e32 v139, s10, v217
	v_lshlrev_b32_e32 v140, 16, v218
	v_and_b32_e32 v141, s10, v218
	v_lshlrev_b32_e32 v142, 16, v219
	v_and_b32_e32 v143, s10, v219
	v_lshlrev_b32_e32 v144, 16, v220
	v_and_b32_e32 v145, s10, v220
	v_lshlrev_b32_e32 v146, 16, v221
	v_and_b32_e32 v147, s10, v221
	v_lshlrev_b32_e32 v148, 16, v222
	v_and_b32_e32 v149, s10, v222
	v_lshlrev_b32_e32 v150, 16, v223
	v_and_b32_e32 v151, s10, v223
	v_pk_mul_f32 v[136:137], v[136:137], v[144:145]
	v_pk_mul_f32 v[138:139], v[138:139], v[146:147]
	v_pk_mul_f32 v[140:141], v[140:141], v[148:149]
	v_pk_mul_f32 v[142:143], v[142:143], v[150:151]
	v_pk_fma_f32 v[236:237], v[24:25], v[136:137], v[236:237]
	v_pk_fma_f32 v[238:239], v[26:27], v[138:139], v[238:239]
	v_pk_fma_f32 v[240:241], v[28:29], v[140:141], v[240:241]
	v_pk_fma_f32 v[242:243], v[30:31], v[142:143], v[242:243]
	v_lshlrev_b32_e32 v144, 16, v228
	v_and_b32_e32 v145, s10, v228
	v_lshlrev_b32_e32 v146, 16, v229
	v_and_b32_e32 v147, s10, v229
	v_lshlrev_b32_e32 v148, 16, v230
	v_and_b32_e32 v149, s10, v230
	v_lshlrev_b32_e32 v150, 16, v231
	v_and_b32_e32 v151, s10, v231
	v_mul_f32_e32 v136, s11, v144
	v_mul_f32_e32 v137, s11, v145
	v_mul_f32_e32 v138, s11, v146
	v_mul_f32_e32 v139, s11, v147
	v_mul_f32_e32 v140, s11, v148
	v_mul_f32_e32 v141, s11, v149
	v_mul_f32_e32 v142, s11, v150
	v_mul_f32_e32 v143, s11, v151
	v_exp_f32_e32 v136, v136
	v_exp_f32_e32 v137, v137
	v_exp_f32_e32 v138, v138
	v_exp_f32_e32 v139, v139
	v_exp_f32_e32 v140, v140
	v_exp_f32_e32 v141, v141
	v_exp_f32_e32 v142, v142
	v_exp_f32_e32 v143, v143
	v_lshlrev_b32_e32 v244, 16, v224
	v_and_b32_e32 v245, s10, v224
	v_lshlrev_b32_e32 v246, 16, v225
	v_and_b32_e32 v247, s10, v225
	v_lshlrev_b32_e32 v248, 16, v226
	v_and_b32_e32 v249, s10, v226
	v_lshlrev_b32_e32 v250, 16, v227
	v_and_b32_e32 v251, s10, v227
	v_add_f32_e32 v136, 1.0, v136
	v_add_f32_e32 v137, 1.0, v137
	v_add_f32_e32 v138, 1.0, v138
	v_add_f32_e32 v139, 1.0, v139
	v_add_f32_e32 v140, 1.0, v140
	v_add_f32_e32 v141, 1.0, v141
	v_add_f32_e32 v142, 1.0, v142
	v_add_f32_e32 v143, 1.0, v143
	v_rcp_f32_e32 v136, v136
	v_rcp_f32_e32 v137, v137
	v_rcp_f32_e32 v138, v138
	v_rcp_f32_e32 v139, v139
	v_rcp_f32_e32 v140, v140
	v_rcp_f32_e32 v141, v141
	v_rcp_f32_e32 v142, v142
	v_rcp_f32_e32 v143, v143
	v_pk_mul_f32 v[244:245], v[244:245], v[236:237]
	v_pk_mul_f32 v[246:247], v[246:247], v[238:239]
	v_pk_mul_f32 v[248:249], v[248:249], v[240:241]
	v_pk_mul_f32 v[250:251], v[250:251], v[242:243]
	v_pk_mul_f32 v[144:145], v[144:145], v[136:137]
	v_pk_mul_f32 v[146:147], v[146:147], v[138:139]
	v_pk_mul_f32 v[148:149], v[148:149], v[140:141]
	v_pk_mul_f32 v[150:151], v[150:151], v[142:143]
	v_pk_mul_f32 v[244:245], v[244:245], v[144:145]
	v_pk_mul_f32 v[246:247], v[246:247], v[146:147]
	v_pk_mul_f32 v[248:249], v[248:249], v[148:149]
	v_pk_mul_f32 v[250:251], v[250:251], v[150:151]
	v_cvt_pk_bf16_f32 v48, v244, v245
	v_cvt_pk_bf16_f32 v49, v246, v247
	v_cvt_pk_bf16_f32 v50, v248, v249
	v_cvt_pk_bf16_f32 v51, v250, v251
	global_store_dwordx4 v232, v[48:51], s[6:7]
	s_waitcnt vmcnt(3)
; __device__ __forceinline__ float bflo(unsigned w) { return __uint_as_float(w << 16); }
; __device__ __forceinline__ float bfhi(unsigned w) { return __uint_as_float(w & 0xffff0000u); }
; __device__ __forceinline__ float silu_f(float x) { return x * rcp_f(1.f + exp_f(-x)); }
; __device__ __forceinline__ u32x4 pack8(const float* v) { u32x4 o; o.x = pk2(v[0], v[1]); o.y = pk2(v[2], v[3]); o.z = pk2(v[4], v[5]); o.w = pk2(v[6], v[7]); return o; }
; __device__ __forceinline__ void conva_prompt(const bf16_t* z, const float* caw, bf16_t* ycat, int gt, int GT) {
;     ...
;         for (int j = 0; j < 3; ++j) {
;             const bool ok = t - 2 + j >= 0; const ptrdiff_t ro = (ptrdiff_t)(ok ? j - 2 : 0) * NZ;
;             u32x4 c = *(const u32x4*)(zr + ro + 1024); const u32x4 hh = *(const u32x4*)(zr + ro + 2048);
;             if (!ok) c = (u32x4){0u, 0u, 0u, 0u};
;             const f32x4 w0 = *(const f32x4*)(caw + j * 1024 + c8), w1 = *(const f32x4*)(caw + j * 1024 + c8 + 4);
;             conv[0] += w0.x * (bflo(c.x) * bflo(hh.x)); conv[1] += w0.y * (bfhi(c.x) * bfhi(hh.x)); conv[2] += w0.z * (bflo(c.y) * bflo(hh.y)); conv[3] += w0.w * (bfhi(c.y) * bfhi(hh.y));
;             conv[4] += w1.x * (bflo(c.z) * bflo(hh.z)); conv[5] += w1.y * (bfhi(c.z) * bfhi(hh.z)); conv[6] += w1.z * (bflo(c.w) * bflo(hh.w)); conv[7] += w1.w * (bfhi(c.w) * bfhi(hh.w));
;         }
;         const u32x4 bb = *(const u32x4*)zr, gg = *(const u32x4*)(zr + 3072);
;         float y[8];
;         y[0] = bflo(bb.x) * conv[0] * silu_f(bflo(gg.x)); y[1] = bfhi(bb.x) * conv[1] * silu_f(bfhi(gg.x)); y[2] = bflo(bb.y) * conv[2] * silu_f(bflo(gg.y)); y[3] = bfhi(bb.y) * conv[3] * silu_f(bfhi(gg.y));
;         y[4] = bflo(bb.z) * conv[4] * silu_f(bflo(gg.z)); y[5] = bfhi(bb.z) * conv[5] * silu_f(bfhi(gg.z)); y[6] = bflo(bb.w) * conv[6] * silu_f(bflo(gg.w)); y[7] = bfhi(bb.w) * conv[7] * silu_f(bfhi(gg.w));
;         *(u32x4*)(ycat + (size_t)row * DM + c8) = pack8(y);
;     }
	v_cmp_lt_u32_e32 vcc, 1, v189
	v_lshlrev_b32_e32 v144, 16, v160
	v_and_b32_e32 v145, s10, v160
	v_lshlrev_b32_e32 v146, 16, v161
	v_and_b32_e32 v147, s10, v161
	v_lshlrev_b32_e32 v148, 16, v162
	v_and_b32_e32 v149, s10, v162
	v_lshlrev_b32_e32 v150, 16, v163
	v_and_b32_e32 v151, s10, v163
	v_cndmask_b32_e32 v156, 0, v156, vcc
	v_cndmask_b32_e32 v157, 0, v157, vcc
	v_cndmask_b32_e32 v158, 0, v158, vcc
	v_cndmask_b32_e32 v159, 0, v159, vcc
	v_cmp_ne_u32_e32 vcc, 0, v189
	v_lshlrev_b32_e32 v136, 16, v156
	v_and_b32_e32 v137, s10, v156
	v_lshlrev_b32_e32 v138, 16, v157
	v_and_b32_e32 v139, s10, v157
	v_lshlrev_b32_e32 v140, 16, v158
	v_and_b32_e32 v141, s10, v158
	v_lshlrev_b32_e32 v142, 16, v159
	v_and_b32_e32 v143, s10, v159
	v_cndmask_b32_e32 v164, 0, v164, vcc
	v_cndmask_b32_e32 v165, 0, v165, vcc
	v_cndmask_b32_e32 v166, 0, v166, vcc
	v_cndmask_b32_e32 v167, 0, v167, vcc
	v_pk_mul_f32 v[136:137], v[136:137], v[144:145]
	v_pk_mul_f32 v[138:139], v[138:139], v[146:147]
	v_pk_mul_f32 v[140:141], v[140:141], v[148:149]
	v_pk_mul_f32 v[142:143], v[142:143], v[150:151]
	v_pk_mul_f32 v[236:237], v[8:9], v[136:137]
	v_pk_mul_f32 v[238:239], v[10:11], v[138:139]
	v_pk_mul_f32 v[240:241], v[12:13], v[140:141]
	v_pk_mul_f32 v[242:243], v[14:15], v[142:143]
	v_lshlrev_b32_e32 v136, 16, v164
	v_and_b32_e32 v137, s10, v164
	v_lshlrev_b32_e32 v138, 16, v165
	v_and_b32_e32 v139, s10, v165
	v_lshlrev_b32_e32 v140, 16, v166
	v_and_b32_e32 v141, s10, v166
	v_lshlrev_b32_e32 v142, 16, v167
	v_and_b32_e32 v143, s10, v167
	v_lshlrev_b32_e32 v144, 16, v168
	v_and_b32_e32 v145, s10, v168
	v_lshlrev_b32_e32 v146, 16, v169
	v_and_b32_e32 v147, s10, v169
	v_lshlrev_b32_e32 v148, 16, v170
	v_and_b32_e32 v149, s10, v170
	v_lshlrev_b32_e32 v150, 16, v171
	v_and_b32_e32 v151, s10, v171
	v_pk_mul_f32 v[136:137], v[136:137], v[144:145]
	v_pk_mul_f32 v[138:139], v[138:139], v[146:147]
	v_pk_mul_f32 v[140:141], v[140:141], v[148:149]
	v_pk_mul_f32 v[142:143], v[142:143], v[150:151]
	v_pk_fma_f32 v[236:237], v[16:17], v[136:137], v[236:237]
	v_pk_fma_f32 v[238:239], v[18:19], v[138:139], v[238:239]
	v_pk_fma_f32 v[240:241], v[20:21], v[140:141], v[240:241]
	v_pk_fma_f32 v[242:243], v[22:23], v[142:143], v[242:243]
	v_lshlrev_b32_e32 v136, 16, v172
	v_and_b32_e32 v137, s10, v172
	v_lshlrev_b32_e32 v138, 16, v173
	v_and_b32_e32 v139, s10, v173
	v_lshlrev_b32_e32 v140, 16, v174
	v_and_b32_e32 v141, s10, v174
	v_lshlrev_b32_e32 v142, 16, v175
	v_and_b32_e32 v143, s10, v175
	v_lshlrev_b32_e32 v144, 16, v176
	v_and_b32_e32 v145, s10, v176
	v_lshlrev_b32_e32 v146, 16, v177
	v_and_b32_e32 v147, s10, v177
	v_lshlrev_b32_e32 v148, 16, v178
	v_and_b32_e32 v149, s10, v178
	v_lshlrev_b32_e32 v150, 16, v179
	v_and_b32_e32 v151, s10, v179
	v_pk_mul_f32 v[136:137], v[136:137], v[144:145]
	v_pk_mul_f32 v[138:139], v[138:139], v[146:147]
	v_pk_mul_f32 v[140:141], v[140:141], v[148:149]
	v_pk_mul_f32 v[142:143], v[142:143], v[150:151]
	v_pk_fma_f32 v[236:237], v[24:25], v[136:137], v[236:237]
	v_pk_fma_f32 v[238:239], v[26:27], v[138:139], v[238:239]
	v_pk_fma_f32 v[240:241], v[28:29], v[140:141], v[240:241]
	v_pk_fma_f32 v[242:243], v[30:31], v[142:143], v[242:243]
	v_lshlrev_b32_e32 v144, 16, v184
	v_and_b32_e32 v145, s10, v184
	v_lshlrev_b32_e32 v146, 16, v185
	v_and_b32_e32 v147, s10, v185
	v_lshlrev_b32_e32 v148, 16, v186
	v_and_b32_e32 v149, s10, v186
	v_lshlrev_b32_e32 v150, 16, v187
	v_and_b32_e32 v151, s10, v187
	v_mul_f32_e32 v136, s11, v144
	v_mul_f32_e32 v137, s11, v145
	v_mul_f32_e32 v138, s11, v146
	v_mul_f32_e32 v139, s11, v147
	v_mul_f32_e32 v140, s11, v148
	v_mul_f32_e32 v141, s11, v149
	v_mul_f32_e32 v142, s11, v150
	v_mul_f32_e32 v143, s11, v151
	v_exp_f32_e32 v136, v136
	v_exp_f32_e32 v137, v137
	v_exp_f32_e32 v138, v138
	v_exp_f32_e32 v139, v139
	v_exp_f32_e32 v140, v140
	v_exp_f32_e32 v141, v141
	v_exp_f32_e32 v142, v142
	v_exp_f32_e32 v143, v143
	v_lshlrev_b32_e32 v244, 16, v180
	v_and_b32_e32 v245, s10, v180
	v_lshlrev_b32_e32 v246, 16, v181
	v_and_b32_e32 v247, s10, v181
	v_lshlrev_b32_e32 v248, 16, v182
	v_and_b32_e32 v249, s10, v182
	v_lshlrev_b32_e32 v250, 16, v183
	v_and_b32_e32 v251, s10, v183
	v_add_f32_e32 v136, 1.0, v136
	v_add_f32_e32 v137, 1.0, v137
	v_add_f32_e32 v138, 1.0, v138
	v_add_f32_e32 v139, 1.0, v139
	v_add_f32_e32 v140, 1.0, v140
	v_add_f32_e32 v141, 1.0, v141
	v_add_f32_e32 v142, 1.0, v142
	v_add_f32_e32 v143, 1.0, v143
	v_rcp_f32_e32 v136, v136
	v_rcp_f32_e32 v137, v137
	v_rcp_f32_e32 v138, v138
	v_rcp_f32_e32 v139, v139
	v_rcp_f32_e32 v140, v140
	v_rcp_f32_e32 v141, v141
	v_rcp_f32_e32 v142, v142
	v_rcp_f32_e32 v143, v143
	v_pk_mul_f32 v[244:245], v[244:245], v[236:237]
	v_pk_mul_f32 v[246:247], v[246:247], v[238:239]
	v_pk_mul_f32 v[248:249], v[248:249], v[240:241]
	v_pk_mul_f32 v[250:251], v[250:251], v[242:243]
	v_pk_mul_f32 v[144:145], v[144:145], v[136:137]
	v_pk_mul_f32 v[146:147], v[146:147], v[138:139]
	v_pk_mul_f32 v[148:149], v[148:149], v[140:141]
	v_pk_mul_f32 v[150:151], v[150:151], v[142:143]
	v_pk_mul_f32 v[244:245], v[244:245], v[144:145]
	v_pk_mul_f32 v[246:247], v[246:247], v[146:147]
	v_pk_mul_f32 v[248:249], v[248:249], v[148:149]
	v_pk_mul_f32 v[250:251], v[250:251], v[150:151]
	v_cvt_pk_bf16_f32 v48, v244, v245
	v_cvt_pk_bf16_f32 v49, v246, v247
	v_cvt_pk_bf16_f32 v50, v248, v249
	v_cvt_pk_bf16_f32 v51, v250, v251
	global_store_dwordx4 v188, v[48:51], s[6:7]
	s_branch .LBB0_415

; __device__ __forceinline__ void conva_prompt(const bf16_t* z, const float* caw, bf16_t* ycat, int gt, int GT) {
; #pragma unroll 2
;     for (int idx = gt; idx < MP * 128; idx += GT) {
;         const int row = idx >> 7, c8 = (idx & 127) * 8, t = row & (SEQ - 1);
;         const bf16_t* zr = z + (size_t)row * NZ + c8;
;         float conv[8];
; #pragma unroll
;         for (int i = 0; i < 8; ++i) conv[i] = 0.f;
; #pragma unroll
;         for (int j = 0; j < 3; ++j) {
;             const bool ok = t - 2 + j >= 0; const ptrdiff_t ro = (ptrdiff_t)(ok ? j - 2 : 0) * NZ;
;             u32x4 c = *(const u32x4*)(zr + ro + 1024); const u32x4 hh = *(const u32x4*)(zr + ro + 2048);
;             if (!ok) c = (u32x4){0u, 0u, 0u, 0u};
;             const f32x4 w0 = *(const f32x4*)(caw + j * 1024 + c8), w1 = *(const f32x4*)(caw + j * 1024 + c8 + 4);
;             conv[0] += w0.x * (bflo(c.x) * bflo(hh.x)); conv[1] += w0.y * (bfhi(c.x) * bfhi(hh.x)); conv[2] += w0.z * (bflo(c.y) * bflo(hh.y)); conv[3] += w0.w * (bfhi(c.y) * bfhi(hh.y));
;             conv[4] += w1.x * (bflo(c.z) * bflo(hh.z)); conv[5] += w1.y * (bfhi(c.z) * bfhi(hh.z)); conv[6] += w1.z * (bflo(c.w) * bflo(hh.w)); conv[7] += w1.w * (bfhi(c.w) * bfhi(hh.w));
;         }
;         const u32x4 bb = *(const u32x4*)zr, gg = *(const u32x4*)(zr + 3072);
;         float y[8];
;         y[0] = bflo(bb.x) * conv[0] * silu_f(bflo(gg.x)); y[1] = bfhi(bb.x) * conv[1] * silu_f(bfhi(gg.x)); y[2] = bflo(bb.y) * conv[2] * silu_f(bflo(gg.y)); y[3] = bfhi(bb.y) * conv[3] * silu_f(bfhi(gg.y));
;         y[4] = bflo(bb.z) * conv[4] * silu_f(bflo(gg.z)); y[5] = bfhi(bb.z) * conv[5] * silu_f(bfhi(gg.z)); y[6] = bflo(bb.w) * conv[6] * silu_f(bflo(gg.w)); y[7] = bfhi(bb.w) * conv[7] * silu_f(bfhi(gg.w));
;         *(u32x4*)(ycat + (size_t)row * DM + c8) = pack8(y);
;     }
; }
; __device__ __forceinline__ void conv_states_prompt(const bf16_t* z, float* oca, float* ocq, int gt, int GT) {
;     for (int idx = gt; idx < NB * 2 * 1024; idx += GT) { const int c = idx & 1023, j = (idx >> 10) & 1, b = idx >> 11;
;         const bf16_t* zr = z + (size_t)(b * SEQ + SEQ - 2 + j) * NZ; oca[idx] = bf2f(zr[1024 + c]) * bf2f(zr[2048 + c]); }
;     for (int idx = gt; idx < NB * 3 * 3072; idx += GT) { const int c = (int)((unsigned)idx % 3072u), j = (int)((unsigned)idx / 3072u) % 3, b = (int)((unsigned)idx / 9216u);
.LBB0_494:
	s_mov_b64 s[4:5], 0x13c00000
	v_lshl_add_u32 v4, s18, 9, v150
	v_lshl_add_u64 v[0:1], v[2:3], 0, s[4:5]
	s_mov_b32 s4, 0x100000
	v_cmp_gt_i32_e32 vcc, s4, v4
	s_and_saveexec_b64 s[6:7], vcc
	s_cbranch_execz .LBB0_497
.LBB0_497:
	s_or_b64 exec, exec, s[6:7]
	v_mov_b64_e32 v[2:3], s[14:15]
	flat_load_dwordx2 v[2:3], v[2:3] offset:144
	v_cmp_gt_i32_e32 vcc, s96, v4
	s_and_saveexec_b64 s[4:5], vcc
	s_mov_b64 s[14:15], 0x60000
	s_cbranch_execz .LBB0_505
	v_and_b32_e32 v5, 0x3ff, v4
	v_lshlrev_b32_e32 v152, 1, v5
	v_max_i32_e32 v5, 0xfffea000, v4
	v_add_u32_e32 v5, 0x8000, v5
	v_sub_u32_e32 v8, v5, v150
	s_lshl_b32 s6, s30, 9
	v_cmp_ne_u32_e32 vcc, s6, v8
	s_waitcnt vmcnt(0) lgkmcnt(0)
	v_lshl_add_u64 v[6:7], v[0:1], 0, v[152:153]
	s_mov_b64 s[8:9], -1
	v_cndmask_b32_e64 v8, 1, 2, vcc
	v_subb_co_u32_e32 v5, vcc, v5, v150, vcc
	v_subrev_u32_e32 v5, s6, v5
	v_mul_hi_u32 v5, v5, s56
	v_add_u32_sdwa v12, v8, v5 dst_sel:DWORD dst_unused:UNUSED_PAD src0_sel:DWORD src1_sel:WORD_1
	v_cmp_lt_u32_e32 vcc, 1, v12
	v_mov_b32_e32 v8, v4
	s_and_saveexec_b64 s[6:7], vcc
	s_cbranch_execz .LBB0_502
	s_lshl_b64 s[8:9], s[92:93], 15
	v_lshl_add_u64 v[8:9], v[2:3], 0, s[8:9]
	s_mov_b64 s[8:9], 0x4100000
	v_and_b32_e32 v13, 0x1fffe, v12
	v_add_u32_e32 v5, 0x18000, v4
	v_lshl_add_u64 v[8:9], v[8:9], 0, s[8:9]
	s_mov_b64 s[8:9], 0
	v_mov_b32_e32 v14, v13
	v_mov_b64_e32 v[10:11], v[4:5]
